# attention loop: x0 score block alternates v[130:145]/v[82:97] per step (register swap over step1 phaseB + step2 phaseA) so the 16 v_mov_b64 copies per iteration are gone; 8 dead post-barrier lgkmcnt w
# speedup vs baseline: 1.0179x; 1.0090x over previous
; #define SBAR() __builtin_amdgcn_sched_barrier(0)
; #define VRD(i) do { if constexpr (VAR & 2) break; lo[(i) & 3] = vtr(vb + v_rd_off((i) >> 2, (i) & 3, 0)); hv[(i) & 3] = vtr(vb + v_rd_off((i) >> 2, (i) & 3, 1)); } while (0)
; template <int VAR> ...
;     ...
;     float ps = 0.f;
;     if constexpr (VAR & 4) { ka[0] = qr[0]; ka[1] = qr[1]; ka[2] = qr[2]; ka[3] = qr[3]; kb[0] = qr[0]; kb[1] = qr[1]; kb[2] = qr[2]; kb[3] = qr[3]; }
;     ka[0] = kp[0]; kb[0] = kp[1]; ka[1] = kp[2]; kb[1] = kp[3]; if (dk) glds16(gk, lk); SBAR();
;     { const f32x16 z = f32x16{};
;       QKM(x0, ka[0], qr[0], z);  SUM4(y0, 0); PKA(y0, 0);       SBAR();
;       QKM(x1, kb[0], qr[0], z);  SUM4(y0, 4); PKB(y0, 4, pa0);  KRD(2); if (dv) glds16(gv, lv); SBAR(); }
;     QKM(x0, ka[1], qr[1], x0); SUM4(y0, 8); PKA(y0, 8);       SBAR();
;     QKM(x1, kb[1], qr[1], x1); SUM4(y0, 12); PKB(y0, 12, pa1); KRD(3); if (dv) glds16(gv + 8192, lv + 8192); SBAR();
;     QKM(x0, ka[2], qr[2], x0); SUM4(y1, 0); PKA(y1, 0);       SBAR();
;     QKM(x1, kb[2], qr[2], x1); SUM4(y1, 4); PKB(y1, 4, pa2);  SBAR();
;     QKM(x0, ka[3], qr[3], x0); SUM4(y1, 8); PKA(y1, 8);       SBAR();
;     QKM(x1, kb[3], qr[3], x1); SUM4(y1, 12); PKB(y1, 12, pa3); VRD(0); VRD(1); SBAR();
;     VRD(2); VRD(3); SBAR();
;     if (near) {
;         float tA[4], uA[4], tB[4], uB[4];
;     ...
;         TLD(tA, uA, 0); SBAR(); TLD(tB, uB, 1); SBAR();
;         asm volatile("s_nop 15\n\ts_nop 7" : "+v"(x0), "+v"(x1));
;         TAD(tA, uA, 0); SBAR(); TLD(tA, uA, 2); SBAR(); TAD(tB, uB, 1); SBAR(); TLD(tB, uB, 3); SBAR(); TAD(tA, uA, 2); SBAR(); TAD(tB, uB, 3);
;     ...
;     } else if (__builtin_expect(shift != 0.f, 0)) {
;         asm volatile("s_nop 15\n\ts_nop 7" : "+v"(x0), "+v"(x1));
; #pragma unroll
;         for (int r = 0; r < 16; ++r) { asm volatile("v_sub_f32 %0, %0, %1" : "+v"(x0[r]) : "v"(shift)); asm volatile("v_sub_f32 %0, %0, %1" : "+v"(x1[r]) : "v"(shift)); }
;     }
;     SBAR();
;     ...
;     GAPB(0, pa0); GAPB(1, pa1); GAPB(2, pa2); GAPB(3, pa3); GAPB(4, pa0); GAPB(5, pa1); GAPB(6, pa2); GAPB(7, pa3);
;     GAPB(8, pa0); GAPB(9, pa1); GAPB(10, pa2); GAPB(11, pa3);
;     if (wv == 3) asm volatile("s_waitcnt vmcnt(3)" ::: "memory"); else if (wv == 2) asm volatile("s_waitcnt vmcnt(2)" ::: "memory"); else asm volatile("s_waitcnt vmcnt(0)" ::: "memory");
;     asm volatile("s_waitcnt lgkmcnt(0)\n\ts_barrier" ::: "memory");
.LBB0_356:
	s_lshl_b32 s0, s67, 13
	s_lshl_b32 s1, s86, 14
	s_add_i32 s90, s20, 1
	s_add_i32 s0, s0, s88
	s_add_i32 s66, s1, s87
	v_lshl_add_u64 v[4:5], v[206:207], 0, s[44:45]
	s_mov_b32 m0, s0
	s_lshl_b32 s92, s91, 13
	global_load_lds_dwordx4 v[4:5], off
	v_add_u32_e32 v12, s92, v215
	s_waitcnt lgkmcnt(3)
	v_mfma_f32_32x32x16_bf16 v[130:145], v[174:177], v[146:149], 0
	v_add_f32_e32 v4, v82, v83
	v_add_f32_e32 v5, v84, v85
	v_add_f32_e32 v6, v4, v5
	v_cvt_pk_bf16_f32 v4, v82, v83
	v_cvt_pk_bf16_f32 v5, v84, v85
	v_add_f32_e32 v7, v86, v87
	v_add_f32_e32 v8, v88, v89
	s_waitcnt lgkmcnt(2)
	v_mfma_f32_32x32x16_bf16 v[114:129], v[170:173], v[146:149], 0
	v_add_f32_e32 v7, v7, v8
	v_add_f32_e32 v8, v7, v6
	v_cvt_pk_bf16_f32 v6, v86, v87
	v_cvt_pk_bf16_f32 v7, v88, v89
	v_add_u32_e32 v9, v12, v218
	s_mov_b32 m0, s66
	ds_read_b128 v[14:17], v9 offset:49152
	ds_read_b128 v[86:89], v9 offset:53248
	global_load_lds_dwordx4 v[208:209], off
	s_waitcnt lgkmcnt(3)
	v_mfma_f32_32x32x16_bf16 v[130:145], v[166:169], v[150:153], v[130:145]
	v_add_f32_e32 v9, v90, v91
	v_add_f32_e32 v10, v92, v93
	v_add_f32_e32 v9, v9, v10
	v_add_f32_e32 v10, v9, v8
	v_cvt_pk_bf16_f32 v8, v90, v91
	v_cvt_pk_bf16_f32 v9, v92, v93
	v_add_f32_e32 v11, v94, v95
	v_add_f32_e32 v13, v96, v97
	s_waitcnt lgkmcnt(2)
	v_mfma_f32_32x32x16_bf16 v[114:129], v[162:165], v[150:153], v[114:129]
	v_add_f32_e32 v11, v11, v13
	v_add_f32_e32 v13, v11, v10
	v_cvt_pk_bf16_f32 v10, v94, v95
	v_cvt_pk_bf16_f32 v11, v96, v97
	v_add_u32_e32 v12, v12, v219
	ds_read_b128 v[90:93], v12 offset:49152
	ds_read_b128 v[82:85], v12 offset:53248
	s_add_i32 m0, s66, 0x2000
	v_lshl_add_u64 v[94:95], v[208:209], 0, s[22:23]
	global_load_lds_dwordx4 v[94:95], off
	s_lshl_b32 s2, s67, 14
	s_sub_i32 s66, s89, 64
	s_cmp_le_i32 s66, s85
	s_waitcnt lgkmcnt(3)
	v_mfma_f32_32x32x16_bf16 v[130:145], v[14:17], v[154:157], v[130:145]
	v_add_f32_e32 v12, v98, v99
	v_add_f32_e32 v94, v100, v101
	v_add_f32_e32 v12, v12, v94
	v_add_f32_e32 v94, v12, v13
	v_cvt_pk_bf16_f32 v12, v98, v99
	v_cvt_pk_bf16_f32 v13, v100, v101
	s_waitcnt lgkmcnt(2)
	v_mfma_f32_32x32x16_bf16 v[114:129], v[86:89], v[154:157], v[114:129]
	v_add_f32_e32 v14, v102, v103
	v_add_f32_e32 v15, v104, v105
	v_add_f32_e32 v14, v14, v15
	v_add_f32_e32 v16, v14, v94
	v_cvt_pk_bf16_f32 v14, v102, v103
	v_cvt_pk_bf16_f32 v15, v104, v105
	s_waitcnt lgkmcnt(1)
	v_mfma_f32_32x32x16_bf16 v[130:145], v[90:93], v[158:161], v[130:145]
	v_add_f32_e32 v17, v106, v107
	v_add_f32_e32 v86, v108, v109
	v_add_f32_e32 v17, v17, v86
	v_add_f32_e32 v16, v17, v16
	v_cvt_pk_bf16_f32 v178, v106, v107
	v_cvt_pk_bf16_f32 v179, v108, v109
	v_add_f32_e32 v17, v110, v111
	v_add_f32_e32 v86, v112, v113
	v_add_f32_e32 v17, v17, v86
	v_add_f32_e32 v229, v17, v16
	v_cvt_pk_bf16_f32 v180, v110, v111
	v_cvt_pk_bf16_f32 v181, v112, v113
	v_add_u32_e32 v16, s2, v214
	s_waitcnt lgkmcnt(0)
	v_mfma_f32_32x32x16_bf16 v[114:129], v[82:85], v[158:161], v[114:129]
	ds_read_b64_tr_b16 v[174:175], v16
	ds_read_b64_tr_b16 v[176:177], v16 offset:256
	ds_read_b64_tr_b16 v[170:171], v16 offset:4096
	ds_read_b64_tr_b16 v[172:173], v16 offset:4352
	ds_read_b64_tr_b16 v[166:167], v16 offset:8192
	ds_read_b64_tr_b16 v[168:169], v16 offset:8448
	ds_read_b64_tr_b16 v[162:163], v16 offset:12288
	ds_read_b64_tr_b16 v[164:165], v16 offset:12544
	s_cbranch_scc0 .Lp2s_near1
	s_and_b64 vcc, exec, s[4:5]
	s_cbranch_vccnz .Lp2t_shift1
.LBB0_367:
	s_waitcnt lgkmcnt(6)
	v_mfma_f32_32x32x16_bf16 v[66:81], v[4:7], v[174:177], v[66:81]
	v_exp_f32_e32 v130, v130
	v_exp_f32_e32 v114, v114
	ds_read_b64_tr_b16 v[98:99], v16 offset:512
	ds_read_b64_tr_b16 v[100:101], v16 offset:768
	s_waitcnt lgkmcnt(6)
	v_mfma_f32_32x32x16_bf16 v[66:81], v[8:11], v[170:173], v[66:81]
	v_exp_f32_e32 v131, v131
	v_exp_f32_e32 v115, v115
	ds_read_b64_tr_b16 v[102:103], v16 offset:4608
	ds_read_b64_tr_b16 v[104:105], v16 offset:4864
	s_waitcnt lgkmcnt(6)
	v_mfma_f32_32x32x16_bf16 v[66:81], v[12:15], v[166:169], v[66:81]
	v_exp_f32_e32 v132, v132
	v_exp_f32_e32 v116, v116
	ds_read_b64_tr_b16 v[106:107], v16 offset:8704
	ds_read_b64_tr_b16 v[108:109], v16 offset:8960
	s_waitcnt lgkmcnt(6)
	v_mfma_f32_32x32x16_bf16 v[66:81], v[178:181], v[162:165], v[66:81]
	v_exp_f32_e32 v133, v133
	v_exp_f32_e32 v117, v117
	ds_read_b64_tr_b16 v[110:111], v16 offset:12800
	ds_read_b64_tr_b16 v[112:113], v16 offset:13056
	s_waitcnt lgkmcnt(6)
	v_mfma_f32_32x32x16_bf16 v[50:65], v[4:7], v[98:101], v[50:65]
	v_exp_f32_e32 v134, v134
	v_exp_f32_e32 v118, v118
	v_exp_f32_e32 v142, v142
	ds_read_b64_tr_b16 v[82:83], v16 offset:1024
	ds_read_b64_tr_b16 v[84:85], v16 offset:1280
	s_waitcnt lgkmcnt(6)
	v_mfma_f32_32x32x16_bf16 v[50:65], v[8:11], v[102:105], v[50:65]
	v_exp_f32_e32 v135, v135
	v_exp_f32_e32 v119, v119
	v_exp_f32_e32 v126, v126
	ds_read_b64_tr_b16 v[86:87], v16 offset:5120
	ds_read_b64_tr_b16 v[88:89], v16 offset:5376
	s_waitcnt lgkmcnt(6)
	v_mfma_f32_32x32x16_bf16 v[50:65], v[12:15], v[106:109], v[50:65]
	v_exp_f32_e32 v136, v136
	v_exp_f32_e32 v120, v120
	v_exp_f32_e32 v143, v143
	ds_read_b64_tr_b16 v[90:91], v16 offset:9216
	ds_read_b64_tr_b16 v[92:93], v16 offset:9472
	s_waitcnt lgkmcnt(6)
	v_mfma_f32_32x32x16_bf16 v[50:65], v[178:181], v[110:113], v[50:65]
	v_exp_f32_e32 v137, v137
	v_exp_f32_e32 v121, v121
	v_exp_f32_e32 v127, v127
	ds_read_b64_tr_b16 v[94:95], v16 offset:13312
	ds_read_b64_tr_b16 v[96:97], v16 offset:13568
	s_waitcnt lgkmcnt(6)
	v_mfma_f32_32x32x16_bf16 v[34:49], v[4:7], v[82:85], v[34:49]
	v_exp_f32_e32 v138, v138
	v_exp_f32_e32 v122, v122
	v_exp_f32_e32 v144, v144
	ds_read_b64_tr_b16 v[98:99], v16 offset:1536
	ds_read_b64_tr_b16 v[100:101], v16 offset:1792
	s_waitcnt lgkmcnt(6)
	v_mfma_f32_32x32x16_bf16 v[34:49], v[8:11], v[86:89], v[34:49]
	v_exp_f32_e32 v139, v139
	v_exp_f32_e32 v123, v123
	v_exp_f32_e32 v128, v128
	ds_read_b64_tr_b16 v[102:103], v16 offset:5632
	ds_read_b64_tr_b16 v[104:105], v16 offset:5888
	s_waitcnt lgkmcnt(6)
	v_mfma_f32_32x32x16_bf16 v[34:49], v[12:15], v[90:93], v[34:49]
	v_exp_f32_e32 v140, v140
	v_exp_f32_e32 v124, v124
	v_exp_f32_e32 v145, v145
	ds_read_b64_tr_b16 v[106:107], v16 offset:9728
	ds_read_b64_tr_b16 v[108:109], v16 offset:9984
	s_waitcnt lgkmcnt(6)
	v_mfma_f32_32x32x16_bf16 v[34:49], v[178:181], v[94:97], v[34:49]
	v_exp_f32_e32 v141, v141
	v_exp_f32_e32 v125, v125
	v_exp_f32_e32 v129, v129
	ds_read_b64_tr_b16 v[110:111], v16 offset:13824
	ds_read_b64_tr_b16 v[112:113], v16 offset:14080
	s_waitcnt vmcnt(3)
	v_lshl_add_u32 v182, s86, 13, v215
	s_waitcnt lgkmcnt(0)
	s_barrier
; #define SBAR() __builtin_amdgcn_sched_barrier(0)
; template <int VAR> ...
;     ...
;     float ps = 0.f;
;     if constexpr (VAR & 4) { ka[0] = qr[0]; ka[1] = qr[1]; ka[2] = qr[2]; ka[3] = qr[3]; kb[0] = qr[0]; kb[1] = qr[1]; kb[2] = qr[2]; kb[3] = qr[3]; }
;     ka[0] = kp[0]; kb[0] = kp[1]; ka[1] = kp[2]; kb[1] = kp[3]; if (dk) glds16(gk, lk); SBAR();
;     { const f32x16 z = f32x16{};
;       QKM(x0, ka[0], qr[0], z);  SUM4(y0, 0); PKA(y0, 0);       SBAR();
;       QKM(x1, kb[0], qr[0], z);  SUM4(y0, 4); PKB(y0, 4, pa0);  KRD(2); if (dv) glds16(gv, lv); SBAR(); }
;     QKM(x0, ka[1], qr[1], x0); SUM4(y0, 8); PKA(y0, 8);       SBAR();
;     QKM(x1, kb[1], qr[1], x1); SUM4(y0, 12); PKB(y0, 12, pa1); KRD(3); if (dv) glds16(gv + 8192, lv + 8192); SBAR();
;     QKM(x0, ka[2], qr[2], x0); SUM4(y1, 0); PKA(y1, 0);       SBAR();
;     QKM(x1, kb[2], qr[2], x1); SUM4(y1, 4); PKB(y1, 4, pa2);  SBAR();
;     QKM(x0, ka[3], qr[3], x0); SUM4(y1, 8); PKA(y1, 8);       SBAR();
;     QKM(x1, kb[3], qr[3], x1); SUM4(y1, 12); PKB(y1, 12, pa3); VRD(0); VRD(1); SBAR();
;     VRD(2); VRD(3); SBAR();
;     if (near) {
;         float tA[4], uA[4], tB[4], uB[4];
;     ...
;         TLD(tA, uA, 0); SBAR(); TLD(tB, uB, 1); SBAR();
;         asm volatile("s_nop 15\n\ts_nop 7" : "+v"(x0), "+v"(x1));
;         TAD(tA, uA, 0); SBAR(); TLD(tA, uA, 2); SBAR(); TAD(tB, uB, 1); SBAR(); TLD(tB, uB, 3); SBAR(); TAD(tA, uA, 2); SBAR(); TAD(tB, uB, 3);
;     ...
;     } else if (__builtin_expect(shift != 0.f, 0)) {
;         asm volatile("s_nop 15\n\ts_nop 7" : "+v"(x0), "+v"(x1));
; #pragma unroll
;         for (int r = 0; r < 16; ++r) { asm volatile("v_sub_f32 %0, %0, %1" : "+v"(x0[r]) : "v"(shift)); asm volatile("v_sub_f32 %0, %0, %1" : "+v"(x1[r]) : "v"(shift)); }
;     }
;     SBAR();
;     ...
;     GAPB(0, pa0); GAPB(1, pa1); GAPB(2, pa2); GAPB(3, pa3); GAPB(4, pa0); GAPB(5, pa1); GAPB(6, pa2); GAPB(7, pa3);
;     GAPB(8, pa0); GAPB(9, pa1); GAPB(10, pa2); GAPB(11, pa3);
;     if (wv == 3) asm volatile("s_waitcnt vmcnt(3)" ::: "memory"); else if (wv == 2) asm volatile("s_waitcnt vmcnt(2)" ::: "memory"); else asm volatile("s_waitcnt vmcnt(0)" ::: "memory");
;     asm volatile("s_waitcnt lgkmcnt(0)\n\ts_barrier" ::: "memory");
;     if (pre) { const char* a0_ = Kn + (((0 + hi) ^ sw) << 4); const char* a1_ = Kn + (((2 + hi) ^ sw) << 4);
	v_add_u32_e32 v16, v182, v216
	v_add_u32_e32 v17, v182, v217
	ds_read_b128 v[174:177], v16 offset:49152
	ds_read_b128 v[170:173], v16 offset:53248
	ds_read_b128 v[166:169], v17 offset:49152
	ds_read_b128 v[162:165], v17 offset:53248
	v_mfma_f32_32x32x16_bf16 v[18:33], v[4:7], v[98:101], v[18:33]
	v_mfma_f32_32x32x16_bf16 v[18:33], v[8:11], v[102:105], v[18:33]
	v_mfma_f32_32x32x16_bf16 v[18:33], v[12:15], v[106:109], v[18:33]
	v_mfma_f32_32x32x16_bf16 v[18:33], v[178:181], v[110:113], v[18:33]
	s_add_i32 s0, s86, 1
	s_cmp_lg_u32 s86, 2
	s_cselect_b32 s68, s0, 0
	s_lshl_b32 s1, s68, 14
	s_add_i32 s20, s20, 2
	s_add_i32 m0, s92, s88
	s_add_i32 s69, s1, s87
	global_load_lds_dwordx4 v[206:207], off
	v_lshl_add_u64 v[12:13], v[208:209], 0, s[26:27]
	s_waitcnt lgkmcnt(3)
	v_mfma_f32_32x32x16_bf16 v[82:97], v[174:177], v[146:149], 0
	v_add_f32_e32 v4, v130, v131
	v_add_f32_e32 v5, v132, v133
	v_add_f32_e32 v6, v4, v5
	v_cvt_pk_bf16_f32 v4, v130, v131
	v_cvt_pk_bf16_f32 v5, v132, v133
	v_add_f32_e32 v7, v134, v135
	v_add_f32_e32 v8, v136, v137
	s_waitcnt lgkmcnt(2)
	v_mfma_f32_32x32x16_bf16 v[98:113], v[170:173], v[146:149], 0
	v_add_f32_e32 v7, v7, v8
	v_add_f32_e32 v8, v7, v6
	v_cvt_pk_bf16_f32 v6, v134, v135
	v_cvt_pk_bf16_f32 v7, v136, v137
	v_add_u32_e32 v9, v182, v218
	s_mov_b32 m0, s69
	ds_read_b128 v[14:17], v9 offset:49152
	ds_read_b128 v[130:133], v9 offset:53248
	global_load_lds_dwordx4 v[12:13], off
	s_waitcnt lgkmcnt(3)
	v_mfma_f32_32x32x16_bf16 v[82:97], v[166:169], v[150:153], v[82:97]
	v_add_f32_e32 v9, v138, v139
	v_add_f32_e32 v10, v140, v141
	v_add_f32_e32 v9, v9, v10
	v_add_f32_e32 v10, v9, v8
	v_cvt_pk_bf16_f32 v8, v138, v139
	v_cvt_pk_bf16_f32 v9, v140, v141
	v_add_f32_e32 v11, v142, v143
	v_add_f32_e32 v134, v144, v145
	s_waitcnt lgkmcnt(2)
	v_mfma_f32_32x32x16_bf16 v[98:113], v[162:165], v[150:153], v[98:113]
	v_add_f32_e32 v11, v11, v134
	v_add_f32_e32 v178, v11, v10
	v_cvt_pk_bf16_f32 v10, v142, v143
	v_cvt_pk_bf16_f32 v11, v144, v145
	v_add_u32_e32 v134, v182, v219
	ds_read_b128 v[138:141], v134 offset:49152
	ds_read_b128 v[134:137], v134 offset:53248
	s_add_i32 m0, s69, 0x2000
	v_lshl_add_u64 v[12:13], v[12:13], 0, s[22:23]
	global_load_lds_dwordx4 v[12:13], off
	s_lshl_b32 s0, s91, 14
	s_cmp_le_i32 s89, s85
	s_waitcnt lgkmcnt(3)
	v_mfma_f32_32x32x16_bf16 v[82:97], v[14:17], v[154:157], v[82:97]
	v_add_f32_e32 v12, v114, v115
	v_add_f32_e32 v13, v116, v117
	v_add_f32_e32 v12, v12, v13
	v_add_f32_e32 v142, v12, v178
	v_cvt_pk_bf16_f32 v12, v114, v115
	v_cvt_pk_bf16_f32 v13, v116, v117
	s_waitcnt lgkmcnt(2)
	v_mfma_f32_32x32x16_bf16 v[98:113], v[130:133], v[154:157], v[98:113]
	v_add_f32_e32 v14, v118, v119
	v_add_f32_e32 v15, v120, v121
	v_add_f32_e32 v14, v14, v15
	v_add_f32_e32 v16, v14, v142
	v_cvt_pk_bf16_f32 v14, v118, v119
	v_cvt_pk_bf16_f32 v15, v120, v121
	s_waitcnt lgkmcnt(1)
	v_mfma_f32_32x32x16_bf16 v[82:97], v[138:141], v[158:161], v[82:97]
	v_add_f32_e32 v17, v122, v123
	v_add_f32_e32 v130, v124, v125
	v_add_f32_e32 v17, v17, v130
	v_add_f32_e32 v16, v17, v16
	v_cvt_pk_bf16_f32 v178, v122, v123
	v_cvt_pk_bf16_f32 v179, v124, v125
	v_add_f32_e32 v17, v126, v127
	v_add_f32_e32 v130, v128, v129
	v_add_f32_e32 v17, v17, v130
	v_add_f32_e32 v16, v17, v16
	v_cvt_pk_bf16_f32 v180, v126, v127
	v_cvt_pk_bf16_f32 v181, v128, v129
	v_add_u32_e32 v17, s0, v214
	s_waitcnt lgkmcnt(0)
	v_mfma_f32_32x32x16_bf16 v[98:113], v[134:137], v[158:161], v[98:113]
	ds_read_b64_tr_b16 v[194:195], v17
	ds_read_b64_tr_b16 v[196:197], v17 offset:256
	ds_read_b64_tr_b16 v[190:191], v17 offset:4096
	ds_read_b64_tr_b16 v[192:193], v17 offset:4352
	ds_read_b64_tr_b16 v[186:187], v17 offset:8192
	ds_read_b64_tr_b16 v[188:189], v17 offset:8448
	ds_read_b64_tr_b16 v[182:183], v17 offset:12288
	ds_read_b64_tr_b16 v[184:185], v17 offset:12544
	s_cbranch_scc0 .Lp2s_near2
	s_and_b64 vcc, exec, s[4:5]
	s_cbranch_vccnz .Lp2t_shift2
.LBB0_385:
	s_waitcnt lgkmcnt(6)
	v_mfma_f32_32x32x16_bf16 v[66:81], v[4:7], v[194:197], v[66:81]
	v_exp_f32_e32 v82, v82
	v_exp_f32_e32 v98, v98
	ds_read_b64_tr_b16 v[114:115], v17 offset:512
	ds_read_b64_tr_b16 v[116:117], v17 offset:768
	s_waitcnt lgkmcnt(6)
	v_mfma_f32_32x32x16_bf16 v[66:81], v[8:11], v[190:193], v[66:81]
	v_exp_f32_e32 v83, v83
	v_exp_f32_e32 v99, v99
	ds_read_b64_tr_b16 v[118:119], v17 offset:4608
	ds_read_b64_tr_b16 v[120:121], v17 offset:4864
	s_waitcnt lgkmcnt(6)
	v_mfma_f32_32x32x16_bf16 v[66:81], v[12:15], v[186:189], v[66:81]
	v_exp_f32_e32 v84, v84
	v_exp_f32_e32 v100, v100
	ds_read_b64_tr_b16 v[122:123], v17 offset:8704
	ds_read_b64_tr_b16 v[124:125], v17 offset:8960
	s_waitcnt lgkmcnt(6)
	v_mfma_f32_32x32x16_bf16 v[66:81], v[178:181], v[182:185], v[66:81]
	v_exp_f32_e32 v85, v85
	v_exp_f32_e32 v101, v101
	ds_read_b64_tr_b16 v[126:127], v17 offset:12800
	ds_read_b64_tr_b16 v[128:129], v17 offset:13056
	s_waitcnt lgkmcnt(6)
	v_mfma_f32_32x32x16_bf16 v[50:65], v[4:7], v[114:117], v[50:65]
	v_exp_f32_e32 v86, v86
	v_exp_f32_e32 v102, v102
	v_exp_f32_e32 v94, v94
	ds_read_b64_tr_b16 v[130:131], v17 offset:1024
	ds_read_b64_tr_b16 v[132:133], v17 offset:1280
	s_waitcnt lgkmcnt(6)
	v_mfma_f32_32x32x16_bf16 v[50:65], v[8:11], v[118:121], v[50:65]
	v_exp_f32_e32 v87, v87
	v_exp_f32_e32 v103, v103
	v_exp_f32_e32 v110, v110
	ds_read_b64_tr_b16 v[134:135], v17 offset:5120
	ds_read_b64_tr_b16 v[136:137], v17 offset:5376
	s_waitcnt lgkmcnt(6)
	v_mfma_f32_32x32x16_bf16 v[50:65], v[12:15], v[122:125], v[50:65]
	v_exp_f32_e32 v88, v88
	v_exp_f32_e32 v104, v104
	v_exp_f32_e32 v95, v95
	ds_read_b64_tr_b16 v[138:139], v17 offset:9216
	ds_read_b64_tr_b16 v[140:141], v17 offset:9472
	s_waitcnt lgkmcnt(6)
	v_mfma_f32_32x32x16_bf16 v[50:65], v[178:181], v[126:129], v[50:65]
	v_exp_f32_e32 v89, v89
	v_exp_f32_e32 v105, v105
	v_exp_f32_e32 v111, v111
	ds_read_b64_tr_b16 v[142:143], v17 offset:13312
	ds_read_b64_tr_b16 v[144:145], v17 offset:13568
	s_waitcnt lgkmcnt(6)
	v_mfma_f32_32x32x16_bf16 v[34:49], v[4:7], v[130:133], v[34:49]
	v_exp_f32_e32 v90, v90
	v_exp_f32_e32 v106, v106
	v_exp_f32_e32 v96, v96
	ds_read_b64_tr_b16 v[114:115], v17 offset:1536
	ds_read_b64_tr_b16 v[116:117], v17 offset:1792
	s_waitcnt lgkmcnt(6)
	v_mfma_f32_32x32x16_bf16 v[34:49], v[8:11], v[134:137], v[34:49]
	v_exp_f32_e32 v91, v91
	v_exp_f32_e32 v107, v107
	v_exp_f32_e32 v112, v112
	ds_read_b64_tr_b16 v[118:119], v17 offset:5632
	ds_read_b64_tr_b16 v[120:121], v17 offset:5888
	s_waitcnt lgkmcnt(6)
	v_mfma_f32_32x32x16_bf16 v[34:49], v[12:15], v[138:141], v[34:49]
	v_exp_f32_e32 v92, v92
	v_exp_f32_e32 v108, v108
	v_exp_f32_e32 v97, v97
	ds_read_b64_tr_b16 v[122:123], v17 offset:9728
	ds_read_b64_tr_b16 v[124:125], v17 offset:9984
	s_waitcnt lgkmcnt(6)
	v_mfma_f32_32x32x16_bf16 v[34:49], v[178:181], v[142:145], v[34:49]
	v_exp_f32_e32 v93, v93
	v_exp_f32_e32 v109, v109
	v_exp_f32_e32 v113, v113
	ds_read_b64_tr_b16 v[126:127], v17 offset:13824
	ds_read_b64_tr_b16 v[128:129], v17 offset:14080
	s_waitcnt vmcnt(3)
	s_waitcnt lgkmcnt(0)
	s_barrier
; #define SBAR() __builtin_amdgcn_sched_barrier(0)
; #define TLD(T, U, g) do { _Pragma("unroll") for (int j = 0; j < 4; ++j) { const int r_ = 4 * (g) + j, c_ = (r_ & 3) + 8 * (r_ >> 2); T[j] = *(const float*)(tabp + 4 * (59 - c_)); U[j] = *(const float*)(tabp + 4 * (59 - c_ - 32)); } } while (0)
; #define TAD(T, U, g) do { _Pragma("unroll") for (int j = 0; j < 4; ++j) { const int r_ = 4 * (g) + j; asm volatile("v_add_f32 %0, %0, %1" : "+v"(x0[r_]) : "v"(T[j])); asm volatile("v_add_f32 %0, %0, %1" : "+v"(x1[r_]) : "v"(U[j])); } } while (0)
; template <int VAR> ...
;     ...
;     if (near) {
;         float tA[4], uA[4], tB[4], uB[4];
;     ...
;         TLD(tA, uA, 0); SBAR(); TLD(tB, uB, 1); SBAR();
;         asm volatile("s_nop 15\n\ts_nop 7" : "+v"(x0), "+v"(x1));
;         TAD(tA, uA, 0); SBAR(); TLD(tA, uA, 2); SBAR(); TAD(tB, uB, 1); SBAR(); TLD(tB, uB, 3); SBAR(); TAD(tA, uA, 2); SBAR(); TAD(tB, uB, 3);
;     ...
;     } else if (__builtin_expect(shift != 0.f, 0)) {
;         asm volatile("s_nop 15\n\ts_nop 7" : "+v"(x0), "+v"(x1));
; #pragma unroll
;         for (int r = 0; r < 16; ++r) { asm volatile("v_sub_f32 %0, %0, %1" : "+v"(x0[r]) : "v"(shift)); asm volatile("v_sub_f32 %0, %0, %1" : "+v"(x1[r]) : "v"(shift)); }
;     }
; template <int VAR>
; __device__ __forceinline__ void dattn_block(const BlockRef& cur, const BlockRef& nxt, bool has_next, char* lds, Seam& S, const Outs& OU) {
;     ...
;     const int TL1 = __builtin_amdgcn_readfirstlane((qlo + 31) / KVBLK + 1);
;     int t = 1;
;     for (; t + 1 < TL1; t += 2) { STEP(pB0, pB1, pA0, pA1, t); STEP(pA0, pA1, pB0, pB1, t + 1); }
	s_cmp_gt_i32 s90, s60
	s_cbranch_scc1 .LBB0_394
	v_lshl_add_u32 v17, s68, 13, v215
	v_add_u32_e32 v130, v17, v216
	v_add_u32_e32 v17, v17, v217
	ds_read_b128 v[174:177], v130 offset:49152
	ds_read_b128 v[170:173], v130 offset:53248
	ds_read_b128 v[166:169], v17 offset:49152
	ds_read_b128 v[162:165], v17 offset:53248
.LBB0_394:
	v_add_f32_e32 v17, v227, v229
	v_mfma_f32_32x32x16_bf16 v[18:33], v[4:7], v[114:117], v[18:33]
	v_mfma_f32_32x32x16_bf16 v[18:33], v[8:11], v[118:121], v[18:33]
	v_mfma_f32_32x32x16_bf16 v[18:33], v[12:15], v[122:125], v[18:33]
	v_mfma_f32_32x32x16_bf16 v[18:33], v[178:181], v[126:129], v[18:33]
	s_add_i32 s0, s68, 1
	s_cmp_lg_u32 s68, 2
	s_cselect_b32 s66, s0, 0
	s_addk_i32 s89, 0x80
	s_add_i32 s62, s20, -1
	v_add_f32_e32 v227, v17, v16
	v_add_u32_e32 v3, 0xfffffe00, v3
	v_lshl_add_u64 v[208:209], v[208:209], 0, s[40:41]
	s_cmp_lt_i32 s62, s60
	v_lshl_add_u64 v[206:207], v[206:207], 0, s[26:27]
	s_cbranch_scc0 .LBB0_403
	s_mov_b32 s67, s86
	s_mov_b32 s91, s68
	s_mov_b32 s86, s66
	s_branch .LBB0_356
.Lp2t_shift1:
	s_nop 15
	s_nop 7
	v_sub_f32_e32 v130, v130, v204
	v_sub_f32_e32 v131, v131, v204
	v_sub_f32_e32 v132, v132, v204
	v_sub_f32_e32 v133, v133, v204
	v_sub_f32_e32 v134, v134, v204
	v_sub_f32_e32 v135, v135, v204
	v_sub_f32_e32 v136, v136, v204
	v_sub_f32_e32 v137, v137, v204
	v_sub_f32_e32 v138, v138, v204
	v_sub_f32_e32 v139, v139, v204
	v_sub_f32_e32 v140, v140, v204
	v_sub_f32_e32 v141, v141, v204
	v_sub_f32_e32 v142, v142, v204
	v_sub_f32_e32 v143, v143, v204
	v_sub_f32_e32 v144, v144, v204
	v_sub_f32_e32 v145, v145, v204
	v_sub_f32_e32 v114, v114, v204
	v_sub_f32_e32 v115, v115, v204
	v_sub_f32_e32 v116, v116, v204
	v_sub_f32_e32 v117, v117, v204
	v_sub_f32_e32 v118, v118, v204
	v_sub_f32_e32 v119, v119, v204
	v_sub_f32_e32 v120, v120, v204
	v_sub_f32_e32 v121, v121, v204
	v_sub_f32_e32 v122, v122, v204
	v_sub_f32_e32 v123, v123, v204
	v_sub_f32_e32 v124, v124, v204
	v_sub_f32_e32 v125, v125, v204
	v_sub_f32_e32 v126, v126, v204
	v_sub_f32_e32 v127, v127, v204
	v_sub_f32_e32 v128, v128, v204
	v_sub_f32_e32 v129, v129, v204
	s_branch .LBB0_367
.Lp2t_shift2:
	s_nop 15
	s_nop 7
	v_sub_f32_e32 v82, v82, v204
	v_sub_f32_e32 v83, v83, v204
	v_sub_f32_e32 v84, v84, v204
	v_sub_f32_e32 v85, v85, v204
	v_sub_f32_e32 v86, v86, v204
	v_sub_f32_e32 v87, v87, v204
	v_sub_f32_e32 v88, v88, v204
	v_sub_f32_e32 v89, v89, v204
	v_sub_f32_e32 v90, v90, v204
	v_sub_f32_e32 v91, v91, v204
	v_sub_f32_e32 v92, v92, v204
	v_sub_f32_e32 v93, v93, v204
	v_sub_f32_e32 v94, v94, v204
	v_sub_f32_e32 v95, v95, v204
	v_sub_f32_e32 v96, v96, v204
	v_sub_f32_e32 v97, v97, v204
	v_sub_f32_e32 v98, v98, v204
	v_sub_f32_e32 v99, v99, v204
	v_sub_f32_e32 v100, v100, v204
	v_sub_f32_e32 v101, v101, v204
	v_sub_f32_e32 v102, v102, v204
	v_sub_f32_e32 v103, v103, v204
	v_sub_f32_e32 v104, v104, v204
	v_sub_f32_e32 v105, v105, v204
	v_sub_f32_e32 v106, v106, v204
	v_sub_f32_e32 v107, v107, v204
	v_sub_f32_e32 v108, v108, v204
	v_sub_f32_e32 v109, v109, v204
	v_sub_f32_e32 v110, v110, v204
	v_sub_f32_e32 v111, v111, v204
	v_sub_f32_e32 v112, v112, v204
	v_sub_f32_e32 v113, v113, v204
	s_branch .LBB0_385
.Lp2s_near1:
	ds_read2_b32 v[82:83], v3 offset0:123 offset1:122
	ds_read2_b32 v[84:85], v3 offset0:121 offset1:120
	ds_read2_b32 v[86:87], v3 offset0:115 offset1:114
	ds_read2_b32 v[88:89], v3 offset0:113 offset1:112
	ds_read2_b32 v[90:91], v3 offset0:107 offset1:106
	ds_read2_b32 v[92:93], v3 offset0:105 offset1:104
	ds_read2_b32 v[94:95], v3 offset0:99 offset1:98
	ds_read2_b32 v[96:97], v3 offset0:97 offset1:96
	s_waitcnt lgkmcnt(8)
	ds_read2_b32 v[98:99], v3 offset0:91 offset1:90
	ds_read2_b32 v[100:101], v3 offset0:89 offset1:88
	ds_read2_b32 v[102:103], v3 offset0:83 offset1:82
	ds_read2_b32 v[104:105], v3 offset0:81 offset1:80
	ds_read2_b32 v[106:107], v3 offset0:75 offset1:74
	ds_read2_b32 v[108:109], v3 offset0:73 offset1:72
	ds_read2_b32 v[110:111], v3 offset0:67 offset1:66
	ds_read2_b32 v[112:113], v3 offset0:65 offset1:64
	s_waitcnt lgkmcnt(8)
	v_add_f32_e32 v130, v130, v82
	v_add_f32_e32 v131, v131, v83
	v_add_f32_e32 v132, v132, v84
	v_add_f32_e32 v133, v133, v85
	v_add_f32_e32 v134, v134, v86
	v_add_f32_e32 v135, v135, v87
	v_add_f32_e32 v136, v136, v88
	v_add_f32_e32 v137, v137, v89
	v_add_f32_e32 v138, v138, v90
	v_add_f32_e32 v139, v139, v91
	v_add_f32_e32 v140, v140, v92
	v_add_f32_e32 v141, v141, v93
	v_add_f32_e32 v142, v142, v94
	v_add_f32_e32 v143, v143, v95
	v_add_f32_e32 v144, v144, v96
	v_add_f32_e32 v145, v145, v97
	s_waitcnt lgkmcnt(0)
	v_add_f32_e32 v114, v114, v98
	v_add_f32_e32 v115, v115, v99
	v_add_f32_e32 v116, v116, v100
	v_add_f32_e32 v117, v117, v101
	v_add_f32_e32 v118, v118, v102
	v_add_f32_e32 v119, v119, v103
	v_add_f32_e32 v120, v120, v104
	v_add_f32_e32 v121, v121, v105
	v_add_f32_e32 v122, v122, v106
	v_add_f32_e32 v123, v123, v107
	v_add_f32_e32 v124, v124, v108
	v_add_f32_e32 v125, v125, v109
	v_add_f32_e32 v126, v126, v110
	v_add_f32_e32 v127, v127, v111
	v_add_f32_e32 v128, v128, v112
	v_add_f32_e32 v129, v129, v113
	s_branch .LBB0_367
.Lp2s_near2:
	ds_read2_b32 v[130:131], v3 offset0:59 offset1:58
	ds_read2_b32 v[132:133], v3 offset0:57 offset1:56
	ds_read2_b32 v[134:135], v3 offset0:51 offset1:50
	ds_read2_b32 v[136:137], v3 offset0:49 offset1:48
	ds_read2_b32 v[138:139], v3 offset0:43 offset1:42
	ds_read2_b32 v[140:141], v3 offset0:41 offset1:40
	ds_read2_b32 v[142:143], v3 offset0:35 offset1:34
	ds_read2_b32 v[144:145], v3 offset0:33 offset1:32
	s_waitcnt lgkmcnt(8)
	ds_read2_b32 v[114:115], v3 offset0:27 offset1:26
	ds_read2_b32 v[116:117], v3 offset0:25 offset1:24
	ds_read2_b32 v[118:119], v3 offset0:19 offset1:18
	ds_read2_b32 v[120:121], v3 offset0:17 offset1:16
	ds_read2_b32 v[122:123], v3 offset0:11 offset1:10
	ds_read2_b32 v[124:125], v3 offset0:9 offset1:8
	ds_read2_b32 v[126:127], v3 offset0:3 offset1:2
	ds_read2_b32 v[128:129], v3 offset0:1 offset1:0
	s_waitcnt lgkmcnt(8)
	v_add_f32_e32 v82, v82, v130
	v_add_f32_e32 v83, v83, v131
	v_add_f32_e32 v84, v84, v132
	v_add_f32_e32 v85, v85, v133
	v_add_f32_e32 v86, v86, v134
	v_add_f32_e32 v87, v87, v135
	v_add_f32_e32 v88, v88, v136
	v_add_f32_e32 v89, v89, v137
	v_add_f32_e32 v90, v90, v138
	v_add_f32_e32 v91, v91, v139
	v_add_f32_e32 v92, v92, v140
	v_add_f32_e32 v93, v93, v141
	v_add_f32_e32 v94, v94, v142
	v_add_f32_e32 v95, v95, v143
	v_add_f32_e32 v96, v96, v144
	v_add_f32_e32 v97, v97, v145
	s_waitcnt lgkmcnt(0)
	v_add_f32_e32 v98, v98, v114
	v_add_f32_e32 v99, v99, v115
	v_add_f32_e32 v100, v100, v116
	v_add_f32_e32 v101, v101, v117
	v_add_f32_e32 v102, v102, v118
	v_add_f32_e32 v103, v103, v119
	v_add_f32_e32 v104, v104, v120
	v_add_f32_e32 v105, v105, v121
	v_add_f32_e32 v106, v106, v122
	v_add_f32_e32 v107, v107, v123
	v_add_f32_e32 v108, v108, v124
	v_add_f32_e32 v109, v109, v125
	v_add_f32_e32 v110, v110, v126
	v_add_f32_e32 v111, v111, v127
	v_add_f32_e32 v112, v112, v128
	v_add_f32_e32 v113, v113, v129
	s_branch .LBB0_385

; #define STAGE_ISSUE(t) do { if ((t) + 2 < NT) DMA_K(Kh, (t) + 2, s_prev); if ((t) + 1 < NT) DMA_V(Vh, (t) + 1, s_next); } while (0)
; template <int VAR>
; __device__ __forceinline__ void dattn_block(const BlockRef& cur, const BlockRef& nxt, bool has_next, char* lds, Seam& S, const Outs& OU) {
;     ...
;     if (t < TL1) {
;         STEP(pB0, pB1, pA0, pA1, t);
;         pA0 = pB0; pA1 = pB1;
;     }
;     ...
;     if (TL1 < NT) STAGE_ISSUE(TL1);
.LBB0_403:
	s_waitcnt lgkmcnt(0)
	s_lshl_b64 s[4:5], s[20:21], 14
	s_cmp_gt_i32 s62, s60
	s_cbranch_scc1 .LBB0_423
